# attention: rescale compare moved above the segment barrier (MFMA-first M head)
# speedup vs baseline: 1.0028x; 1.0028x over previous
.LBB0_399:
	v_cmp_gt_f32_e32 vcc, 1.0, v215
	s_barrier
	s_cbranch_vccz .LBB0_403
	s_and_saveexec_b64 s[66:67], s[4:5]
	ds_write_b32 v212, v215 offset:128
	s_or_b64 exec, exec, s[66:67]
	s_waitcnt lgkmcnt(0)
	v_add_u32_e32 v146, s73, v207
	ds_read_b128 v[158:161], v146 offset:224
	ds_read_b128 v[154:157], v146 offset:192
	ds_read_b128 v[150:153], v146 offset:160
	ds_read_b128 v[146:149], v146 offset:128
	s_waitcnt lgkmcnt(3)
	v_pk_mul_f32 v[126:127], v[126:127], v[158:159]
	s_waitcnt lgkmcnt(2)
	v_pk_mul_f32 v[122:123], v[122:123], v[154:155]
	s_waitcnt lgkmcnt(1)
	v_pk_mul_f32 v[118:119], v[118:119], v[150:151]
	v_pk_mul_f32 v[128:129], v[128:129], v[160:161]
	v_pk_mul_f32 v[124:125], v[124:125], v[156:157]
	v_pk_mul_f32 v[120:121], v[120:121], v[152:153]
	s_waitcnt lgkmcnt(0)
	v_pk_mul_f32 v[116:117], v[116:117], v[148:149]
	v_pk_mul_f32 v[114:115], v[114:115], v[146:147]
	v_pk_mul_f32 v[110:111], v[110:111], v[158:159]
	v_pk_mul_f32 v[106:107], v[106:107], v[154:155]
	v_pk_mul_f32 v[102:103], v[102:103], v[150:151]
	v_pk_mul_f32 v[112:113], v[112:113], v[160:161]
	v_pk_mul_f32 v[108:109], v[108:109], v[156:157]
	v_pk_mul_f32 v[104:105], v[104:105], v[152:153]
	v_pk_mul_f32 v[100:101], v[100:101], v[148:149]
	v_pk_mul_f32 v[98:99], v[98:99], v[146:147]
	v_pk_mul_f32 v[94:95], v[94:95], v[158:159]
	v_pk_mul_f32 v[90:91], v[90:91], v[154:155]
	v_pk_mul_f32 v[86:87], v[86:87], v[150:151]
	v_pk_mul_f32 v[96:97], v[96:97], v[160:161]
	v_pk_mul_f32 v[92:93], v[92:93], v[156:157]
	v_pk_mul_f32 v[88:89], v[88:89], v[152:153]
	v_pk_mul_f32 v[84:85], v[84:85], v[148:149]
	v_pk_mul_f32 v[82:83], v[82:83], v[146:147]
	v_pk_mul_f32 v[78:79], v[78:79], v[158:159]
	v_pk_mul_f32 v[74:75], v[74:75], v[154:155]
	v_pk_mul_f32 v[70:71], v[70:71], v[150:151]
	v_pk_mul_f32 v[80:81], v[80:81], v[160:161]
	v_pk_mul_f32 v[76:77], v[76:77], v[156:157]
	v_pk_mul_f32 v[72:73], v[72:73], v[152:153]
	v_pk_mul_f32 v[68:69], v[68:69], v[148:149]
	v_pk_mul_f32 v[66:67], v[66:67], v[146:147]
	v_pk_mul_f32 v[62:63], v[62:63], v[158:159]
	v_pk_mul_f32 v[58:59], v[58:59], v[154:155]
	v_pk_mul_f32 v[54:55], v[54:55], v[150:151]
	v_pk_mul_f32 v[64:65], v[64:65], v[160:161]
	v_pk_mul_f32 v[60:61], v[60:61], v[156:157]
	v_pk_mul_f32 v[56:57], v[56:57], v[152:153]
	v_pk_mul_f32 v[52:53], v[52:53], v[148:149]
	v_pk_mul_f32 v[50:51], v[50:51], v[146:147]
	v_pk_mul_f32 v[46:47], v[46:47], v[158:159]
	v_pk_mul_f32 v[42:43], v[42:43], v[154:155]
	v_pk_mul_f32 v[38:39], v[38:39], v[150:151]
	v_pk_mul_f32 v[48:49], v[48:49], v[160:161]
	v_pk_mul_f32 v[44:45], v[44:45], v[156:157]
	v_pk_mul_f32 v[40:41], v[40:41], v[152:153]
	v_pk_mul_f32 v[36:37], v[36:37], v[148:149]
	v_pk_mul_f32 v[34:35], v[34:35], v[146:147]
	v_pk_mul_f32 v[30:31], v[30:31], v[158:159]
	v_pk_mul_f32 v[26:27], v[26:27], v[154:155]
	v_pk_mul_f32 v[22:23], v[22:23], v[150:151]
	v_pk_mul_f32 v[32:33], v[32:33], v[160:161]
	v_pk_mul_f32 v[28:29], v[28:29], v[156:157]
	v_pk_mul_f32 v[24:25], v[24:25], v[152:153]
	v_pk_mul_f32 v[20:21], v[20:21], v[148:149]
	v_pk_mul_f32 v[18:19], v[18:19], v[146:147]
	v_pk_mul_f32 v[14:15], v[14:15], v[158:159]
	v_pk_mul_f32 v[10:11], v[10:11], v[154:155]
	v_pk_mul_f32 v[6:7], v[6:7], v[150:151]
	v_pk_mul_f32 v[16:17], v[16:17], v[160:161]
	v_pk_mul_f32 v[12:13], v[12:13], v[156:157]
	v_pk_mul_f32 v[8:9], v[8:9], v[152:153]
	v_pk_mul_f32 v[4:5], v[4:5], v[148:149]
	v_pk_mul_f32 v[2:3], v[2:3], v[146:147]

.LBB0_419:
	v_cmp_gt_f32_e32 vcc, 1.0, v218
	s_barrier
	s_cbranch_vccz .LBB0_423
	s_and_saveexec_b64 s[8:9], s[4:5]
	ds_write_b32 v212, v218 offset:128
	s_or_b64 exec, exec, s[8:9]
	s_waitcnt lgkmcnt(0)
	v_add_u32_e32 v146, s73, v207
	ds_read_b128 v[158:161], v146 offset:224
	ds_read_b128 v[154:157], v146 offset:192
	ds_read_b128 v[150:153], v146 offset:160
	ds_read_b128 v[146:149], v146 offset:128
	s_waitcnt lgkmcnt(3)
	v_pk_mul_f32 v[126:127], v[126:127], v[158:159]
	s_waitcnt lgkmcnt(2)
	v_pk_mul_f32 v[122:123], v[122:123], v[154:155]
	s_waitcnt lgkmcnt(1)
	v_pk_mul_f32 v[118:119], v[118:119], v[150:151]
	v_pk_mul_f32 v[128:129], v[128:129], v[160:161]
	v_pk_mul_f32 v[124:125], v[124:125], v[156:157]
	v_pk_mul_f32 v[120:121], v[120:121], v[152:153]
	s_waitcnt lgkmcnt(0)
	v_pk_mul_f32 v[116:117], v[116:117], v[148:149]
	v_pk_mul_f32 v[114:115], v[114:115], v[146:147]
	v_pk_mul_f32 v[110:111], v[110:111], v[158:159]
	v_pk_mul_f32 v[106:107], v[106:107], v[154:155]
	v_pk_mul_f32 v[102:103], v[102:103], v[150:151]
	v_pk_mul_f32 v[112:113], v[112:113], v[160:161]
	v_pk_mul_f32 v[108:109], v[108:109], v[156:157]
	v_pk_mul_f32 v[104:105], v[104:105], v[152:153]
	v_pk_mul_f32 v[100:101], v[100:101], v[148:149]
	v_pk_mul_f32 v[98:99], v[98:99], v[146:147]
	v_pk_mul_f32 v[94:95], v[94:95], v[158:159]
	v_pk_mul_f32 v[90:91], v[90:91], v[154:155]
	v_pk_mul_f32 v[86:87], v[86:87], v[150:151]
	v_pk_mul_f32 v[96:97], v[96:97], v[160:161]
	v_pk_mul_f32 v[92:93], v[92:93], v[156:157]
	v_pk_mul_f32 v[88:89], v[88:89], v[152:153]
	v_pk_mul_f32 v[84:85], v[84:85], v[148:149]
	v_pk_mul_f32 v[82:83], v[82:83], v[146:147]
	v_pk_mul_f32 v[78:79], v[78:79], v[158:159]
	v_pk_mul_f32 v[74:75], v[74:75], v[154:155]
	v_pk_mul_f32 v[70:71], v[70:71], v[150:151]
	v_pk_mul_f32 v[80:81], v[80:81], v[160:161]
	v_pk_mul_f32 v[76:77], v[76:77], v[156:157]
	v_pk_mul_f32 v[72:73], v[72:73], v[152:153]
	v_pk_mul_f32 v[68:69], v[68:69], v[148:149]
	v_pk_mul_f32 v[66:67], v[66:67], v[146:147]
	v_pk_mul_f32 v[62:63], v[62:63], v[158:159]
	v_pk_mul_f32 v[58:59], v[58:59], v[154:155]
	v_pk_mul_f32 v[54:55], v[54:55], v[150:151]
	v_pk_mul_f32 v[64:65], v[64:65], v[160:161]
	v_pk_mul_f32 v[60:61], v[60:61], v[156:157]
	v_pk_mul_f32 v[56:57], v[56:57], v[152:153]
	v_pk_mul_f32 v[52:53], v[52:53], v[148:149]
	v_pk_mul_f32 v[50:51], v[50:51], v[146:147]
	v_pk_mul_f32 v[46:47], v[46:47], v[158:159]
	v_pk_mul_f32 v[42:43], v[42:43], v[154:155]
	v_pk_mul_f32 v[38:39], v[38:39], v[150:151]
	v_pk_mul_f32 v[48:49], v[48:49], v[160:161]
	v_pk_mul_f32 v[44:45], v[44:45], v[156:157]
	v_pk_mul_f32 v[40:41], v[40:41], v[152:153]
	v_pk_mul_f32 v[36:37], v[36:37], v[148:149]
	v_pk_mul_f32 v[34:35], v[34:35], v[146:147]
	v_pk_mul_f32 v[30:31], v[30:31], v[158:159]
	v_pk_mul_f32 v[26:27], v[26:27], v[154:155]
	v_pk_mul_f32 v[22:23], v[22:23], v[150:151]
	v_pk_mul_f32 v[32:33], v[32:33], v[160:161]
	v_pk_mul_f32 v[28:29], v[28:29], v[156:157]
	v_pk_mul_f32 v[24:25], v[24:25], v[152:153]
	v_pk_mul_f32 v[20:21], v[20:21], v[148:149]
	v_pk_mul_f32 v[18:19], v[18:19], v[146:147]
	v_pk_mul_f32 v[14:15], v[14:15], v[158:159]
	v_pk_mul_f32 v[10:11], v[10:11], v[154:155]
	v_pk_mul_f32 v[6:7], v[6:7], v[150:151]
	v_pk_mul_f32 v[16:17], v[16:17], v[160:161]
	v_pk_mul_f32 v[12:13], v[12:13], v[156:157]
	v_pk_mul_f32 v[8:9], v[8:9], v[152:153]
	v_pk_mul_f32 v[4:5], v[4:5], v[148:149]
	v_pk_mul_f32 v[2:3], v[2:3], v[146:147]
